# first-phase norm1 rows: all 16 loads issued at once (same restructuring as the other two norm copies)
# speedup vs baseline: 1.0216x; 1.0005x over previous
.LBB0_531:
	s_andn2_b64 vcc, exec, s[20:21]
	s_cbranch_vccnz .LBB0_528
	s_load_dwordx2 s[20:21], s[26:27], 0x0
	v_add_u32_e32 v4, s28, v3
	v_ashrrev_i32_e32 v5, 31, v4
	v_ashrrev_i32_e32 v0, 12, v4
	v_lshl_add_u64 v[6:7], v[4:5], 0, s[22:23]
	v_add_u32_e32 v0, 1, v0
	v_lshlrev_b64 v[6:7], 12, v[6:7]
	v_cndmask_b32_e64 v0, v0, 0, s[12:13]
	v_and_b32_e32 v24, 0xfc, v2
	s_waitcnt lgkmcnt(0)
	v_lshl_add_u64 v[6:7], s[20:21], 0, v[6:7]
	v_add_u32_e32 v8, s24, v0
	v_lshlrev_b32_e32 v0, 2, v24
	v_lshl_add_u64 v[2:3], v[6:7], 0, v[0:1]
	v_mov_b64_e32 v[6:7], s[34:35]
	s_movk_i32 s20, 0x6000
	v_cmp_lt_i32_e32 vcc, v199, v221
	v_mad_i64_i32 v[6:7], s[20:21], v8, s20, v[6:7]
	s_nop 0
	v_cndmask_b32_e32 v8, v220, v199, vcc
	v_cmp_lt_i32_e32 vcc, v200, v221
	v_lshlrev_b32_e32 v50, 2, v8
	v_lshlrev_b64 v[4:5], 11, v[4:5]
	v_cndmask_b32_e32 v8, v220, v200, vcc
	v_cmp_lt_i32_e32 vcc, v201, v221
	v_lshlrev_b32_e32 v51, 2, v8
	v_lshl_add_u64 v[22:23], s[72:73], 0, v[4:5]
	v_cndmask_b32_e32 v8, v220, v201, vcc
	v_cmp_lt_i32_e32 vcc, v235, v221
	v_lshlrev_b32_e32 v52, 2, v8
	v_lshl_add_u64 v[4:5], v[6:7], 0, s[8:9]
	v_cndmask_b32_e32 v8, v220, v235, vcc
	v_cmp_lt_i32_e32 vcc, v226, v221
	v_lshlrev_b32_e32 v53, 2, v8
	v_lshl_add_u64 v[18:19], v[4:5], 0, v[0:1]
	v_cndmask_b32_e32 v8, v220, v226, vcc
	v_cmp_lt_i32_e32 vcc, v227, v221
	v_lshlrev_b32_e32 v54, 2, v8
	v_lshl_add_u64 v[26:27], v[6:7], 0, v[0:1]
	v_cndmask_b32_e32 v8, v220, v227, vcc
	v_lshlrev_b32_e32 v55, 2, v8
	v_mov_b32_e32 v60, v26
	v_mov_b32_e32 v61, v27
	v_mov_b32_e32 v62, v18
	v_mov_b32_e32 v63, v19
	global_load_dwordx4 v[66:69], v[2:3], off
	global_load_dwordx4 v[70:73], v[2:3], off offset:1024
	global_load_dwordx4 v[74:77], v[2:3], off offset:2048
	global_load_dwordx4 v[78:81], v[2:3], off offset:3072
	global_load_dwordx4 v[82:85], v0, s[4:5]
	global_load_dwordx4 v[86:89], v0, s[4:5] offset:1024
	global_load_dwordx4 v[90:93], v0, s[4:5] offset:2048
	global_load_dwordx4 v[94:97], v0, s[4:5] offset:3072
	global_load_dwordx4 v[98:101], v[60:61], off
	global_load_dwordx4 v[102:105], v[60:61], off offset:1024
	global_load_dwordx4 v[106:109], v[60:61], off offset:2048
	global_load_dwordx4 v[110:113], v[60:61], off offset:3072
	global_load_dwordx4 v[114:117], v[62:63], off
	global_load_dwordx4 v[118:121], v[62:63], off offset:1024
	global_load_dwordx4 v[122:125], v[62:63], off offset:2048
	global_load_dwordx4 v[126:129], v[62:63], off offset:3072
	v_lshlrev_b32_e32 v28, 1, v24
	v_mov_b32_e32 v29, v1
	v_lshl_add_u64 v[26:27], v[22:23], 0, v[28:29]
	s_waitcnt vmcnt(12)
	v_pk_mul_f32 v[130:131], v[66:67], v[66:67]
	v_pk_fma_f32 v[130:131], v[68:69], v[68:69], v[130:131]
	v_pk_fma_f32 v[130:131], v[70:71], v[70:71], v[130:131]
	v_pk_fma_f32 v[130:131], v[72:73], v[72:73], v[130:131]
	v_pk_fma_f32 v[130:131], v[74:75], v[74:75], v[130:131]
	v_pk_fma_f32 v[130:131], v[76:77], v[76:77], v[130:131]
	v_pk_fma_f32 v[130:131], v[78:79], v[78:79], v[130:131]
	v_pk_fma_f32 v[130:131], v[80:81], v[80:81], v[130:131]
	s_nop 0
	v_add_f32_e32 v44, v130, v131
	ds_bpermute_b32 v45, v50, v44
	s_waitcnt lgkmcnt(0)
	v_add_f32_e32 v44, v44, v45
	ds_bpermute_b32 v45, v51, v44
	s_waitcnt lgkmcnt(0)
	v_add_f32_e32 v44, v44, v45
	ds_bpermute_b32 v45, v52, v44
	s_waitcnt lgkmcnt(0)
	v_add_f32_e32 v44, v44, v45
	ds_bpermute_b32 v45, v53, v44
	s_waitcnt lgkmcnt(0)
	v_add_f32_e32 v44, v44, v45
	ds_bpermute_b32 v45, v54, v44
	s_waitcnt lgkmcnt(0)
	v_add_f32_e32 v44, v44, v45
	ds_bpermute_b32 v45, v55, v44
	s_waitcnt lgkmcnt(0)
	v_add_f32_e32 v44, v44, v45
	v_fmamk_f32 v44, v44, 0x3a800000, v187
	v_cmp_gt_f32_e32 vcc, s82, v44
	v_mul_f32_e32 v45, 0x4b800000, v44
	s_nop 0
	v_cndmask_b32_e32 v44, v44, v45, vcc
	v_rsq_f32_e32 v44, v44
	s_nop 0
	v_mul_f32_e32 v45, 0x45800000, v44
	v_cndmask_b32_e32 v44, v44, v45, vcc
	s_waitcnt vmcnt(0)
	v_pk_mul_f32 v[66:67], v[66:67], v[44:45] op_sel_hi:[1,0]
	v_pk_mul_f32 v[68:69], v[68:69], v[44:45] op_sel_hi:[1,0]
	v_pk_add_f32 v[114:115], v[114:115], 1.0 op_sel_hi:[1,0]
	v_pk_add_f32 v[116:117], v[116:117], 1.0 op_sel_hi:[1,0]
	v_pk_mul_f32 v[66:67], v[82:83], v[66:67]
	v_pk_mul_f32 v[68:69], v[84:85], v[68:69]
	v_pk_fma_f32 v[98:99], v[114:115], v[66:67], v[98:99]
	v_pk_fma_f32 v[100:101], v[68:69], v[116:117], v[100:101]
	s_nop 0
	v_cvt_pk_bf16_f32 v98, v98, v99
	v_cvt_pk_bf16_f32 v99, v100, v101
	global_store_dwordx2 v[26:27], v[98:99], off
	v_pk_mul_f32 v[70:71], v[70:71], v[44:45] op_sel_hi:[1,0]
	v_pk_mul_f32 v[72:73], v[72:73], v[44:45] op_sel_hi:[1,0]
	v_pk_add_f32 v[118:119], v[118:119], 1.0 op_sel_hi:[1,0]
	v_pk_add_f32 v[120:121], v[120:121], 1.0 op_sel_hi:[1,0]
	v_pk_mul_f32 v[70:71], v[86:87], v[70:71]
	v_pk_mul_f32 v[72:73], v[88:89], v[72:73]
	v_pk_fma_f32 v[102:103], v[118:119], v[70:71], v[102:103]
	v_pk_fma_f32 v[104:105], v[72:73], v[120:121], v[104:105]
	s_nop 0
	v_cvt_pk_bf16_f32 v102, v102, v103
	v_cvt_pk_bf16_f32 v103, v104, v105
	global_store_dwordx2 v[26:27], v[102:103], off offset:512
	v_pk_mul_f32 v[74:75], v[74:75], v[44:45] op_sel_hi:[1,0]
	v_pk_mul_f32 v[76:77], v[76:77], v[44:45] op_sel_hi:[1,0]
	v_pk_add_f32 v[122:123], v[122:123], 1.0 op_sel_hi:[1,0]
	v_pk_add_f32 v[124:125], v[124:125], 1.0 op_sel_hi:[1,0]
	v_pk_mul_f32 v[74:75], v[90:91], v[74:75]
	v_pk_mul_f32 v[76:77], v[92:93], v[76:77]
	v_pk_fma_f32 v[106:107], v[122:123], v[74:75], v[106:107]
	v_pk_fma_f32 v[108:109], v[76:77], v[124:125], v[108:109]
	s_nop 0
	v_cvt_pk_bf16_f32 v106, v106, v107
	v_cvt_pk_bf16_f32 v107, v108, v109
	global_store_dwordx2 v[26:27], v[106:107], off offset:1024
	v_pk_mul_f32 v[78:79], v[78:79], v[44:45] op_sel_hi:[1,0]
	v_pk_mul_f32 v[80:81], v[80:81], v[44:45] op_sel_hi:[1,0]
	v_pk_add_f32 v[126:127], v[126:127], 1.0 op_sel_hi:[1,0]
	v_pk_add_f32 v[128:129], v[128:129], 1.0 op_sel_hi:[1,0]
	v_pk_mul_f32 v[78:79], v[94:95], v[78:79]
	v_pk_mul_f32 v[80:81], v[96:97], v[80:81]
	v_pk_fma_f32 v[110:111], v[126:127], v[78:79], v[110:111]
	v_pk_fma_f32 v[112:113], v[80:81], v[128:129], v[112:113]
	s_nop 0
	v_cvt_pk_bf16_f32 v110, v110, v111
	v_cvt_pk_bf16_f32 v111, v112, v113
	global_store_dwordx2 v[26:27], v[110:111], off offset:1536
	s_branch .LBB0_528
